# hand-written bf16 GEMM epilogue now also for kind 0 (root cause of the earlier nondeterminism: the epilogue must restore the two kernel-wide constants s96/s97 that the tile dispatch overwrites)
# baseline (speedup 1.0000x reference)
.Lg_bf_epi:
	s_waitcnt vmcnt(0) lgkmcnt(0)
	v_add_u32_e32 v66, s11, v113
	v_add_u32_e32 v70, s29, v115
	s_lshl_b32 s98, s64, 1
	s_lshl_b32 s99, s64, 5
	v_mul_lo_u32 v72, v70, s98
	v_lshl_add_u32 v72, v66, 1, v72
	v_add_u32_e32 v73, s98, v72
	v_add_u32_e32 v74, s98, v73
	v_add_u32_e32 v75, s98, v74
	v_add_u32_e32 v76, s99, v72
	v_add_u32_e32 v77, s98, v76
	v_add_u32_e32 v78, s98, v77
	v_add_u32_e32 v79, s98, v78
	v_add_u32_e32 v80, s99, v76
	v_add_u32_e32 v81, s98, v80
	v_add_u32_e32 v82, s98, v81
	v_add_u32_e32 v83, s98, v82
	v_add_u32_e32 v84, s99, v80
	v_add_u32_e32 v85, s98, v84
	v_add_u32_e32 v86, s98, v85
	v_add_u32_e32 v87, s98, v86
	v_cvt_pk_bf16_f32 v88, v62, v63
	global_store_short v72, v88, s[48:49]
	global_store_short_d16_hi v73, v88, s[48:49]
	v_cvt_pk_bf16_f32 v89, v64, v65
	global_store_short v74, v89, s[48:49]
	global_store_short_d16_hi v75, v89, s[48:49]
	v_cvt_pk_bf16_f32 v90, v58, v59
	global_store_short v72, v90, s[48:49] offset:32
	global_store_short_d16_hi v73, v90, s[48:49] offset:32
	v_cvt_pk_bf16_f32 v91, v60, v61
	global_store_short v74, v91, s[48:49] offset:32
	global_store_short_d16_hi v75, v91, s[48:49] offset:32
	v_cvt_pk_bf16_f32 v92, v54, v55
	global_store_short v72, v92, s[48:49] offset:64
	global_store_short_d16_hi v73, v92, s[48:49] offset:64
	v_cvt_pk_bf16_f32 v93, v56, v57
	global_store_short v74, v93, s[48:49] offset:64
	global_store_short_d16_hi v75, v93, s[48:49] offset:64
	v_cvt_pk_bf16_f32 v94, v50, v51
	global_store_short v72, v94, s[48:49] offset:96
	global_store_short_d16_hi v73, v94, s[48:49] offset:96
	v_cvt_pk_bf16_f32 v95, v52, v53
	global_store_short v74, v95, s[48:49] offset:96
	global_store_short_d16_hi v75, v95, s[48:49] offset:96
	v_cvt_pk_bf16_f32 v88, v46, v47
	global_store_short v76, v88, s[48:49]
	global_store_short_d16_hi v77, v88, s[48:49]
	v_cvt_pk_bf16_f32 v89, v48, v49
	global_store_short v78, v89, s[48:49]
	global_store_short_d16_hi v79, v89, s[48:49]
	v_cvt_pk_bf16_f32 v90, v42, v43
	global_store_short v76, v90, s[48:49] offset:32
	global_store_short_d16_hi v77, v90, s[48:49] offset:32
	v_cvt_pk_bf16_f32 v91, v44, v45
	global_store_short v78, v91, s[48:49] offset:32
	global_store_short_d16_hi v79, v91, s[48:49] offset:32
	v_cvt_pk_bf16_f32 v92, v38, v39
	global_store_short v76, v92, s[48:49] offset:64
	global_store_short_d16_hi v77, v92, s[48:49] offset:64
	v_cvt_pk_bf16_f32 v93, v40, v41
	global_store_short v78, v93, s[48:49] offset:64
	global_store_short_d16_hi v79, v93, s[48:49] offset:64
	v_cvt_pk_bf16_f32 v94, v34, v35
	global_store_short v76, v94, s[48:49] offset:96
	global_store_short_d16_hi v77, v94, s[48:49] offset:96
	v_cvt_pk_bf16_f32 v95, v36, v37
	global_store_short v78, v95, s[48:49] offset:96
	global_store_short_d16_hi v79, v95, s[48:49] offset:96
	v_cvt_pk_bf16_f32 v88, v30, v31
	global_store_short v80, v88, s[48:49]
	global_store_short_d16_hi v81, v88, s[48:49]
	v_cvt_pk_bf16_f32 v89, v32, v33
	global_store_short v82, v89, s[48:49]
	global_store_short_d16_hi v83, v89, s[48:49]
	v_cvt_pk_bf16_f32 v90, v26, v27
	global_store_short v80, v90, s[48:49] offset:32
	global_store_short_d16_hi v81, v90, s[48:49] offset:32
	v_cvt_pk_bf16_f32 v91, v28, v29
	global_store_short v82, v91, s[48:49] offset:32
	global_store_short_d16_hi v83, v91, s[48:49] offset:32
	v_cvt_pk_bf16_f32 v92, v22, v23
	global_store_short v80, v92, s[48:49] offset:64
	global_store_short_d16_hi v81, v92, s[48:49] offset:64
	v_cvt_pk_bf16_f32 v93, v24, v25
	global_store_short v82, v93, s[48:49] offset:64
	global_store_short_d16_hi v83, v93, s[48:49] offset:64
	v_cvt_pk_bf16_f32 v94, v18, v19
	global_store_short v80, v94, s[48:49] offset:96
	global_store_short_d16_hi v81, v94, s[48:49] offset:96
	v_cvt_pk_bf16_f32 v95, v20, v21
	global_store_short v82, v95, s[48:49] offset:96
	global_store_short_d16_hi v83, v95, s[48:49] offset:96
	v_cvt_pk_bf16_f32 v88, v12, v13
	global_store_short v84, v88, s[48:49]
	global_store_short_d16_hi v85, v88, s[48:49]
	v_cvt_pk_bf16_f32 v89, v14, v15
	global_store_short v86, v89, s[48:49]
	global_store_short_d16_hi v87, v89, s[48:49]
	v_cvt_pk_bf16_f32 v90, v8, v9
	global_store_short v84, v90, s[48:49] offset:32
	global_store_short_d16_hi v85, v90, s[48:49] offset:32
	v_cvt_pk_bf16_f32 v91, v10, v11
	global_store_short v86, v91, s[48:49] offset:32
	global_store_short_d16_hi v87, v91, s[48:49] offset:32
	v_cvt_pk_bf16_f32 v92, v4, v5
	global_store_short v84, v92, s[48:49] offset:64
	global_store_short_d16_hi v85, v92, s[48:49] offset:64
	v_cvt_pk_bf16_f32 v93, v6, v7
	global_store_short v86, v93, s[48:49] offset:64
	global_store_short_d16_hi v87, v93, s[48:49] offset:64
	v_cvt_pk_bf16_f32 v94, v0, v1
	global_store_short v84, v94, s[48:49] offset:96
	global_store_short_d16_hi v85, v94, s[48:49] offset:96
	v_cvt_pk_bf16_f32 v95, v2, v3
	global_store_short v86, v95, s[48:49] offset:96
	global_store_short_d16_hi v87, v95, s[48:49] offset:96
	s_waitcnt vmcnt(0)
	s_movk_i32 s96, 0x1000
	s_movk_i32 s97, 0x2000
	s_branch .LBB0_1041

.LBB0_1080:
	s_cmp_eq_u64 s[34:35], 0
	s_cbranch_scc1 .Lg_bf_epi
	s_cmp_lg_u64 s[34:35], 0
	s_cselect_b64 s[4:5], -1, 0
	s_waitcnt vmcnt(7)
	v_add_u32_e32 v66, s11, v113
	v_cndmask_b32_e64 v69, 0, 1, s[4:5]
	s_waitcnt vmcnt(5)
	v_add_u32_e32 v74, s29, v115
	v_cmp_gt_i32_e64 s[6:7], s52, v66
	v_ashrrev_i32_e32 v67, 31, v66
	v_add_u32_e32 v68, s80, v66
	v_cmp_ne_u32_e64 s[4:5], 1, v69
	s_and_saveexec_b64 s[8:9], s[6:7]
	s_cbranch_execz .LBB0_1101
	v_ashrrev_i32_e32 v69, 31, v68
	s_and_b64 vcc, exec, s[4:5]
	v_lshl_add_u64 v[70:71], v[66:67], 2, s[34:35]
	s_cbranch_vccnz .LBB0_1673
	s_andn2_b64 vcc, exec, s[36:37]
	v_mov_b32_e32 v72, v62
	s_cbranch_vccnz .LBB0_1084
	s_load_dwordx2 s[10:11], s[14:15], 0xb0
	s_waitcnt lgkmcnt(0)
	v_lshl_add_u64 v[72:73], v[68:69], 2, s[10:11]
	global_load_dword v72, v[72:73], off
	s_waitcnt vmcnt(0)
	v_mov_b32_e32 v248, v72
	v_add_f32_e32 v73, v62, v72
	v_max_f32_e32 v72, 0, v73
	v_mul_f32_e64 v73, |v73|, s73
	v_exp_f32_e32 v73, v73
	s_nop 0
	v_add_f32_e32 v75, 1.0, v73
	v_add_f32_e32 v76, -1.0, v75
	v_sub_f32_e32 v77, v76, v75
	v_add_f32_e32 v77, 1.0, v77
	v_sub_f32_e32 v76, v73, v76
	v_add_f32_e32 v78, v76, v77
	v_frexp_mant_f32_e32 v76, v75
	v_cmp_gt_f32_e32 vcc, s46, v76
	v_cvt_f64_f32_e32 v[76:77], v75
	v_frexp_exp_i32_f64_e32 v76, v[76:77]
	v_subbrev_co_u32_e32 v84, vcc, 0, v76, vcc
	v_sub_u32_e32 v76, 0, v84
	v_ldexp_f32 v75, v75, v76
	v_ldexp_f32 v76, v78, v76
	v_add_f32_e32 v78, -1.0, v75
	v_add_f32_e32 v77, 1.0, v78
	v_sub_f32_e32 v77, v75, v77
	v_add_f32_e32 v79, v76, v77
	v_add_f32_e32 v77, 1.0, v75
	v_add_f32_e32 v80, -1.0, v77
	v_sub_f32_e32 v75, v75, v80
	v_add_f32_e32 v75, v76, v75
	v_add_f32_e32 v85, v77, v75
	v_rcp_f32_e32 v86, v85
	v_sub_f32_e32 v76, v85, v77
	v_add_f32_e32 v77, v78, v79
	v_sub_f32_e32 v75, v75, v76
	v_mul_f32_e32 v88, v77, v86
	v_sub_f32_e32 v76, v77, v78
	v_mul_f32_e32 v78, v85, v88
	v_fma_f32 v80, v88, v85, -v78
	v_fmac_f32_e32 v80, v88, v75
	v_sub_f32_e32 v87, v79, v76
	v_add_f32_e32 v76, v78, v80
	v_sub_f32_e32 v79, v77, v76
	v_pk_add_f32 v[82:83], v[76:77], v[78:79] neg_lo:[0,1] neg_hi:[0,1]
	v_mov_b32_e32 v81, v76
	v_pk_add_f32 v[76:77], v[82:83], v[80:81] neg_lo:[0,1] neg_hi:[0,1]
	v_cmp_neq_f32_e32 vcc, s0, v73
	v_add_f32_e32 v77, v87, v77
	v_add_f32_e32 v76, v76, v77
	v_add_f32_e32 v77, v79, v76
	v_mul_f32_e32 v87, v86, v77
	v_mul_f32_e32 v78, v85, v87
	v_fma_f32 v80, v87, v85, -v78
	v_fmac_f32_e32 v80, v87, v75
	v_sub_f32_e32 v75, v79, v77
	v_add_f32_e32 v75, v76, v75
	v_add_f32_e32 v76, v78, v80
	v_sub_f32_e32 v79, v77, v76
	v_pk_add_f32 v[82:83], v[76:77], v[78:79] neg_lo:[0,1] neg_hi:[0,1]
	v_mov_b32_e32 v81, v76
	v_pk_add_f32 v[76:77], v[82:83], v[80:81] neg_lo:[0,1] neg_hi:[0,1]
	s_nop 0
	v_add_f32_e32 v75, v75, v77
	v_add_f32_e32 v75, v76, v75
	v_add_f32_e32 v77, v88, v87
	v_add_f32_e32 v75, v79, v75
	v_sub_f32_e32 v76, v77, v88
	v_mul_f32_e32 v75, v86, v75
	v_sub_f32_e32 v76, v87, v76
	v_add_f32_e32 v75, v76, v75
	v_add_f32_e32 v78, v77, v75
	v_mul_f32_e32 v80, v78, v78
	v_fmamk_f32 v76, v80, 0x3e9b6dac, v210
	v_fmaak_f32 v121, v80, v76, 0x3f2aaada
	v_cvt_f32_i32_e32 v76, v84
	v_sub_f32_e32 v77, v78, v77
	v_sub_f32_e32 v75, v75, v77
	v_mul_f32_e32 v77, v78, v80
	v_pk_mul_f32 v[80:81], v[76:77], v[120:121]
	v_ldexp_f32 v79, v78, 1
	v_fma_f32 v78, v76, s1, -v80
	v_fmac_f32_e32 v78, 0xb102e308, v76
	v_pk_add_f32 v[76:77], v[80:81], v[78:79]
	v_ldexp_f32 v75, v75, 1
	v_sub_f32_e32 v79, v77, v79
	v_sub_f32_e32 v79, v81, v79
	v_add_f32_e32 v83, v75, v79
	v_mov_b32_e32 v82, v80
	v_pk_add_f32 v[80:81], v[76:77], v[80:81] neg_lo:[0,1] neg_hi:[0,1]
	v_pk_add_f32 v[84:85], v[76:77], v[82:83]
	v_mov_b32_e32 v79, v76
	v_mov_b32_e32 v81, v85
	v_pk_add_f32 v[86:87], v[78:79], v[80:81] neg_lo:[0,1] neg_hi:[0,1]
	v_pk_add_f32 v[78:79], v[78:79], v[80:81]
	v_mov_b32_e32 v82, v83
	v_pk_add_f32 v[80:81], v[78:79], v[76:77] op_sel:[1,0] op_sel_hi:[0,1] neg_lo:[0,1] neg_hi:[0,1]
	v_pk_add_f32 v[88:89], v[84:85], v[80:81] op_sel_hi:[1,0] neg_lo:[0,1] neg_hi:[0,1]
	v_mov_b32_e32 v84, v85
	v_mov_b32_e32 v85, v79
	v_pk_mov_b32 v[80:81], v[76:77], v[80:81] op_sel:[1,0]
	v_mov_b32_e32 v83, v76
	v_pk_add_f32 v[80:81], v[84:85], v[80:81] neg_lo:[0,1] neg_hi:[0,1]
	v_mov_b32_e32 v88, v86
	v_pk_add_f32 v[76:77], v[82:83], v[80:81] neg_lo:[0,1] neg_hi:[0,1]
	v_mov_b32_e32 v87, v79
	v_pk_add_f32 v[80:81], v[88:89], v[76:77]
	s_nop 0
	v_pk_add_f32 v[82:83], v[80:81], v[80:81] op_sel:[0,1] op_sel_hi:[1,0]
	s_nop 0
	v_pk_add_f32 v[78:79], v[78:79], v[82:83] op_sel:[1,0] op_sel_hi:[0,1]
	v_mov_b32_e32 v81, v78
	v_pk_add_f32 v[84:85], v[80:81], v[86:87] neg_lo:[0,1] neg_hi:[0,1]
	v_mov_b32_e32 v77, v82
	v_sub_f32_e32 v75, v80, v84
	v_pk_add_f32 v[76:77], v[76:77], v[84:85] neg_lo:[0,1] neg_hi:[0,1]
	v_sub_f32_e32 v75, v86, v75
	v_add_f32_e32 v75, v76, v75
	v_add_f32_e32 v75, v75, v77
	v_add_f32_e32 v75, v78, v75
	v_cndmask_b32_e32 v75, v224, v75, vcc
	v_cmp_ngt_f32_e32 vcc, -1.0, v73
	s_nop 1
	v_cndmask_b32_e32 v75, v225, v75, vcc
	v_cmp_neq_f32_e32 vcc, -1.0, v73
	s_nop 1
	v_cndmask_b32_e32 v75, v226, v75, vcc
	v_cmp_lt_f32_e64 vcc, |v73|, s56
	s_nop 1
	v_cndmask_b32_e32 v73, v75, v73, vcc
	v_add_f32_e32 v72, v72, v73
